# baseline (speedup 1.0000x reference)
; __device__ __forceinline__ float fast_exp2(float x) { return __builtin_amdgcn_exp2f(x); }
; __device__ __forceinline__ void df_block(const Params& P, int l, int b, int qrow_blk, int h, int tk_lo, int tk_hi, char* smem) {
;     ...
;   for (int tk = tk_lo; tk < tk_hi; tk += 64) {
;     const int tn = (tk + 64 < tk_hi) ? tk + 64 : tk;
;     rk0 = *(const uint4*)(KD + (size_t)key_row(b, tn + lrow0) * 384 + h * 64 + lch * 8);
;     rk1 = *(const uint4*)(KD + (size_t)key_row(b, tn + lrow0 + 32) * 384 + h * 64 + lch * 8);
;     rv0 = *(const uint4*)(vsrc0 + tn);
;     rv1 = *(const uint4*)(vsrc1 + tn);
;     __builtin_amdgcn_sched_barrier(0);
;     const char* Ks = smem + cur * DF_BUF;
;     const char* Vs = Ks + DF_KBYTES;
; #pragma unroll
;     for (int sub = 0; sub < 2; ++sub) {
;       const char* kp = Ks + (sub * 32 + ql) * DF_KSTR + hh * 16;
;       bf16x8 pa0, pa1, pb0, pb1;
;       {
;         f32x16 S = mfma32(*(const bf16x8*)(kp), q1[0], cini);
;         S = mfma32(*(const bf16x8*)(kp + 32), q1[1], S);
;         float p[16];
; #pragma unroll
;         for (int j = 0; j < 16; ++j) { p[j] = fast_exp2(S[j]); l1 += p[j]; }
;         pack_p(p, pa0, pa1);
;       }
;       {
;         f32x16 S = mfma32(*(const bf16x8*)(kp + 64), q2[0], cini);
;         S = mfma32(*(const bf16x8*)(kp + 96), q2[1], S);
;         float p[16];
; #pragma unroll
;         for (int j = 0; j < 16; ++j) { p[j] = fast_exp2(S[j]); l2 += p[j]; }
;         pack_p(p, pb0, pb1);
;       }
; #pragma unroll
;       for (int s2 = 0; s2 < 2; ++s2) {
;         const char* vp0 = Vs + ql * DF_VSTR + (sub * 32 + 16 * s2 + 4 * hh) * 2;
;         const char* vp1 = vp0 + 32 * DF_VSTR;
;         union { uint4 u; bf16x8 v; } c0, c1;
;         uint2 a0 = *(const uint2*)(vp0), a1 = *(const uint2*)(vp0 + 16);
;         uint2 e0 = *(const uint2*)(vp1), e1 = *(const uint2*)(vp1 + 16);
;         c0.u = make_uint4(a0.x, a0.y, a1.x, a1.y);
;         c1.u = make_uint4(e0.x, e0.y, e1.x, e1.y);
;         o1[0] = mfma32(c0.v, s2 ? pa1 : pa0, o1[0]);
;         o1[1] = mfma32(c1.v, s2 ? pa1 : pa0, o1[1]);
;         o2[0] = mfma32(c0.v, s2 ? pb1 : pb0, o2[0]);
;         o2[1] = mfma32(c1.v, s2 ? pb1 : pb0, o2[1]);
;       }
;     }
.LBB0_405:
	s_add_i32 s15, s17, 64
	s_cmpk_lt_u32 s17, 0x10c0
	s_cselect_b64 s[0:1], -1, 0
	s_and_b64 vcc, s[0:1], exec
	s_cselect_b32 s10, s15, s17
	v_add_u32_e32 v86, s10, v137
	v_cmp_gt_u32_e64 s[0:1], s31, v86
	s_lshl_b64 s[18:19], s[10:11], 1
	v_lshl_add_u64 v[82:83], v[170:171], 0, s[18:19]
	v_cndmask_b32_e64 v87, v235, v165, s[0:1]
	v_cmp_gt_u32_e64 s[0:1], s34, v86
	v_add_u32_e32 v87, v87, v86
	v_lshl_add_u64 v[84:85], v[172:173], 0, s[18:19]
	v_cndmask_b32_e64 v88, v163, v138, s[0:1]
	v_add_u32_e32 v86, v88, v86
	global_load_dwordx4 v[118:121], v[82:83], off
	global_load_dwordx4 v[114:117], v[84:85], off
	v_mad_i64_i32 v[82:83], s[0:1], v87, s29, v[174:175]
	v_mad_i64_i32 v[84:85], s[0:1], v86, s29, v[174:175]
	global_load_dwordx4 v[122:125], v[82:83], off
	global_load_dwordx4 v[126:129], v[84:85], off
	s_mul_i32 s0, s14, 0x4600
	s_xor_b32 s14, s14, 1
	v_or_b32_e32 v82, s0, v140
	v_add3_u32 v218, s0, v223, v136
	s_mul_i32 s0, s14, 0x4600
	v_add_u32_e32 v236, s0, v141
	v_add_u32_e32 v219, v82, v224
	v_add_u32_e32 v237, s0, v143
	v_add_u32_e32 v238, 0x2400, v236
	s_setprio 1
	ds_read_b128 v[176:179], v219
	ds_read_b128 v[180:183], v219 offset:32
	ds_read_b128 v[196:199], v219 offset:64
	v_add_u32_e32 v239, 0x2000, v218
	v_add_u32_e32 v248, 0x3000, v218
	s_waitcnt lgkmcnt(2)
	v_mfma_f32_32x32x16_bf16 v[82:97], v[176:179], v[98:101], v[50:65]
	s_waitcnt lgkmcnt(1)
	v_mfma_f32_32x32x16_bf16 v[82:97], v[180:183], v[102:105], v[82:97]
	s_nop 11
	v_exp_f32_e32 v132, v82
	v_exp_f32_e32 v200, v83
	v_exp_f32_e32 v202, v84
	v_exp_f32_e32 v204, v85
	v_exp_f32_e32 v206, v86
	v_exp_f32_e32 v208, v87
	v_exp_f32_e32 v210, v88
	v_exp_f32_e32 v212, v89
	v_exp_f32_e32 v214, v90
	v_exp_f32_e32 v216, v91
	v_exp_f32_e32 v186, v92
	v_exp_f32_e32 v184, v93
	v_exp_f32_e32 v182, v94
	v_exp_f32_e32 v180, v95
	v_exp_f32_e32 v178, v96
	v_exp_f32_e32 v176, v97
	s_waitcnt lgkmcnt(0)
	v_mfma_f32_32x32x16_bf16 v[82:97], v[196:199], v[106:109], v[50:65]
	ds_read_b128 v[196:199], v219 offset:96
	v_cvt_pk_bf16_f32 v188, v132, v200
	v_cvt_pk_bf16_f32 v189, v202, v204
	v_cvt_pk_bf16_f32 v190, v206, v208
	v_cvt_pk_bf16_f32 v191, v210, v212
	v_cvt_pk_bf16_f32 v192, v214, v216
	v_cvt_pk_bf16_f32 v193, v186, v184
	s_waitcnt lgkmcnt(0)
	v_mfma_f32_32x32x16_bf16 v[82:97], v[196:199], v[110:113], v[82:97]
	v_cvt_pk_bf16_f32 v194, v182, v180
	v_cvt_pk_bf16_f32 v195, v178, v176
	s_nop 11
	v_exp_f32_e32 v215, v90
	v_exp_f32_e32 v217, v91
	v_exp_f32_e32 v187, v92
	v_exp_f32_e32 v185, v93
	v_exp_f32_e32 v183, v94
	v_exp_f32_e32 v181, v95
	v_exp_f32_e32 v179, v96
	v_exp_f32_e32 v177, v97
	ds_read2_b64 v[90:93], v239 offset0:128 offset1:130
	ds_read2_b64 v[94:97], v239 offset0:132 offset1:134
	ds_read2_b64 v[196:199], v248 offset0:160 offset1:162
	v_exp_f32_e32 v133, v82
	v_exp_f32_e32 v201, v83
	v_exp_f32_e32 v203, v84
	v_exp_f32_e32 v205, v85
	v_exp_f32_e32 v207, v86
	v_exp_f32_e32 v209, v87
	v_exp_f32_e32 v211, v88
	v_exp_f32_e32 v213, v89
	v_cvt_pk_bf16_f32 v82, v133, v201
	v_cvt_pk_bf16_f32 v83, v203, v205
	v_cvt_pk_bf16_f32 v84, v207, v209
	v_cvt_pk_bf16_f32 v85, v211, v213
	s_waitcnt lgkmcnt(0)
	v_mfma_f32_32x32x16_bf16 v[2:17], v[196:199], v[188:191], v[2:17]
	v_cvt_pk_bf16_f32 v86, v215, v217
	v_cvt_pk_bf16_f32 v87, v187, v185
	v_cvt_pk_bf16_f32 v88, v183, v181
	v_cvt_pk_bf16_f32 v89, v179, v177
	ds_read_b128 v[244:247], v219 offset:4672
	v_mfma_f32_32x32x16_bf16 v[66:81], v[90:93], v[82:85], v[66:81]
	v_mfma_f32_32x32x16_bf16 v[18:33], v[196:199], v[82:85], v[18:33]
	ds_read2_b64 v[82:85], v248 offset0:164 offset1:166
	s_waitcnt lgkmcnt(0)
	v_mfma_f32_32x32x16_bf16 v[2:17], v[82:85], v[192:195], v[2:17]
	v_mfma_f32_32x32x16_bf16 v[18:33], v[82:85], v[86:89], v[18:33]
	v_add_f32_e64 v82, v130, v132
	v_add_f32_e64 v83, v131, v133
	ds_read_b128 v[130:133], v219 offset:4608
	v_add_f32_e64 v82, v200, v82
	v_add_f32_e64 v83, v201, v83
	v_add_f32_e32 v82, v202, v82
	v_add_f32_e32 v83, v203, v83
	s_nop 0
	v_add_f32_e32 v82, v204, v82
	v_add_f32_e32 v83, v205, v83
	v_mfma_f32_32x32x16_bf16 v[34:49], v[90:93], v[188:191], v[34:49]
	v_add_f32_e64 v82, v206, v82
	v_add_f32_e64 v83, v207, v83
	v_add_f32_e64 v82, v208, v82
	v_add_f32_e64 v83, v209, v83
	v_add_f32_e64 v82, v210, v82
	v_add_f32_e64 v83, v211, v83
	v_add_f32_e32 v82, v212, v82
	v_add_f32_e32 v83, v213, v83
	v_mfma_f32_32x32x16_bf16 v[34:49], v[94:97], v[192:195], v[34:49]
	v_add_f32_e64 v82, v214, v82
	v_add_f32_e64 v83, v215, v83
	v_add_f32_e64 v188, v216, v82
	v_add_f32_e64 v189, v217, v83
	v_mfma_f32_32x32x16_bf16 v[66:81], v[94:97], v[86:89], v[66:81]
	s_waitcnt lgkmcnt(0)
	v_mfma_f32_32x32x16_bf16 v[82:97], v[130:133], v[98:101], v[50:65]
	ds_read_b128 v[130:133], v219 offset:4640
	s_waitcnt lgkmcnt(0)
	v_mfma_f32_32x32x16_bf16 v[82:97], v[130:133], v[102:105], v[82:97]
	s_nop 11
	v_exp_f32_e32 v220, v82
	v_exp_f32_e32 v218, v83
	v_exp_f32_e32 v216, v84
	v_exp_f32_e32 v214, v85
	v_exp_f32_e32 v212, v86
	v_exp_f32_e32 v210, v87
	v_exp_f32_e32 v208, v88
	v_exp_f32_e32 v206, v89
	v_exp_f32_e32 v204, v90
	v_exp_f32_e32 v202, v91
	v_exp_f32_e32 v200, v92
	v_exp_f32_e32 v198, v93
	v_exp_f32_e32 v196, v94
	v_exp_f32_e32 v194, v95
	v_exp_f32_e32 v192, v96
	v_exp_f32_e32 v190, v97
	v_mfma_f32_32x32x16_bf16 v[82:97], v[244:247], v[106:109], v[50:65]
	ds_read_b128 v[244:247], v219 offset:4704
	v_cvt_pk_bf16_f32 v240, v220, v218
	v_cvt_pk_bf16_f32 v241, v216, v214
	v_cvt_pk_bf16_f32 v242, v212, v210
	v_cvt_pk_bf16_f32 v243, v208, v206
	v_cvt_pk_bf16_f32 v130, v204, v202
	v_cvt_pk_bf16_f32 v131, v200, v198
	s_waitcnt lgkmcnt(0)
; __device__ __forceinline__ float fast_exp2(float x) { return __builtin_amdgcn_exp2f(x); }
; __device__ __forceinline__ void df_block(const Params& P, int l, int b, int qrow_blk, int h, int tk_lo, int tk_hi, char* smem) {
;     ...
;         S = mfma32(*(const bf16x8*)(kp + 96), q2[1], S);
;         float p[16];
; #pragma unroll
;         for (int j = 0; j < 16; ++j) { p[j] = fast_exp2(S[j]); l2 += p[j]; }
;         pack_p(p, pb0, pb1);
;       }
; #pragma unroll
;       for (int s2 = 0; s2 < 2; ++s2) {
;         const char* vp0 = Vs + ql * DF_VSTR + (sub * 32 + 16 * s2 + 4 * hh) * 2;
;         const char* vp1 = vp0 + 32 * DF_VSTR;
;         union { uint4 u; bf16x8 v; } c0, c1;
;         uint2 a0 = *(const uint2*)(vp0), a1 = *(const uint2*)(vp0 + 16);
;         uint2 e0 = *(const uint2*)(vp1), e1 = *(const uint2*)(vp1 + 16);
;         c0.u = make_uint4(a0.x, a0.y, a1.x, a1.y);
;         c1.u = make_uint4(e0.x, e0.y, e1.x, e1.y);
;         o1[0] = mfma32(c0.v, s2 ? pa1 : pa0, o1[0]);
;         o1[1] = mfma32(c1.v, s2 ? pa1 : pa0, o1[1]);
;         o2[0] = mfma32(c0.v, s2 ? pb1 : pb0, o2[0]);
;         o2[1] = mfma32(c1.v, s2 ? pb1 : pb0, o2[1]);
;       }
;     }
;     __builtin_amdgcn_sched_barrier(0);
;     {
;       char* d = smem + (cur ^ 1) * DF_BUF;
;       *(uint4*)(d + koff0) = rk0;
;       *(uint4*)(d + koff1) = rk1;
;       *(uint2*)(d + voff0) = make_uint2(rv0.x, rv0.y); *(uint2*)(d + voff0 + 8) = make_uint2(rv0.z, rv0.w);
;       *(uint2*)(d + voff1) = make_uint2(rv1.x, rv1.y); *(uint2*)(d + voff1 + 8) = make_uint2(rv1.z, rv1.w);
;     }
;     __syncthreads();
;     cur ^= 1;
;   }
;   l1 += __shfl_xor(l1, 32);
;   l2 += __shfl_xor(l2, 32);
;   const float r1 = 1.f / l1, r2 = lam / l2;
;   float ss = 0.f;
; #pragma unroll
;   for (int m = 0; m < 2; ++m)
; #pragma unroll
;     for (int j = 0; j < 16; ++j) {
;       float v = o1[m][j] * r1 - o2[m][j] * r2;
;       o1[m][j] = v;
;       ss += v * v;
;     }
;   ss += __shfl_xor(ss, 32);
;   const float rinv = rsqrtf(ss * (1.f / 64.f) + EPS) * (1.f - lam_init);
	v_mfma_f32_32x32x16_bf16 v[82:97], v[244:247], v[110:113], v[82:97]
	v_cvt_pk_bf16_f32 v132, v196, v194
	v_cvt_pk_bf16_f32 v133, v192, v190
	s_nop 11
	v_exp_f32_e32 v205, v90
	v_exp_f32_e32 v203, v91
	v_exp_f32_e32 v201, v92
	v_exp_f32_e32 v199, v93
	v_exp_f32_e32 v197, v94
	v_exp_f32_e32 v195, v95
	v_exp_f32_e32 v193, v96
	v_exp_f32_e32 v191, v97
	ds_read2_b64 v[90:93], v239 offset0:136 offset1:138
	ds_read2_b64 v[94:97], v248 offset0:168 offset1:170
	v_exp_f32_e32 v221, v82
	v_exp_f32_e32 v219, v83
	v_exp_f32_e32 v217, v84
	v_exp_f32_e32 v215, v85
	v_exp_f32_e32 v213, v86
	v_exp_f32_e32 v211, v87
	v_exp_f32_e32 v209, v88
	v_exp_f32_e32 v207, v89
	v_cvt_pk_bf16_f32 v86, v221, v219
	v_cvt_pk_bf16_f32 v87, v217, v215
	v_cvt_pk_bf16_f32 v88, v213, v211
	v_cvt_pk_bf16_f32 v89, v209, v207
	s_waitcnt lgkmcnt(1)
	v_mfma_f32_32x32x16_bf16 v[34:49], v[90:93], v[240:243], v[34:49]
	v_cvt_pk_bf16_f32 v82, v205, v203
	v_cvt_pk_bf16_f32 v83, v201, v199
	v_cvt_pk_bf16_f32 v84, v197, v195
	v_cvt_pk_bf16_f32 v85, v193, v191
	v_mfma_f32_32x32x16_bf16 v[66:81], v[90:93], v[86:89], v[66:81]
	s_waitcnt lgkmcnt(0)
	v_mfma_f32_32x32x16_bf16 v[18:33], v[94:97], v[86:89], v[18:33]
	ds_read2_b64 v[86:89], v239 offset0:140 offset1:142
	ds_read2_b64 v[90:93], v248 offset0:172 offset1:174
	s_waitcnt lgkmcnt(1)
	v_mfma_f32_32x32x16_bf16 v[66:81], v[86:89], v[82:85], v[66:81]
	s_waitcnt lgkmcnt(0)
	v_mfma_f32_32x32x16_bf16 v[18:33], v[90:93], v[82:85], v[18:33]
	v_add_f32_e64 v82, v186, v188
	v_add_f32_e64 v83, v187, v189
	v_add_f32_e64 v82, v184, v82
	v_add_f32_e64 v83, v185, v83
	v_add_f32_e64 v82, v182, v82
	v_add_f32_e64 v83, v183, v83
	v_add_f32_e32 v82, v180, v82
	v_add_f32_e32 v83, v181, v83
	v_mfma_f32_32x32x16_bf16 v[2:17], v[94:97], v[240:243], v[2:17]
	v_add_f32_e64 v82, v178, v82
	v_add_f32_e64 v83, v179, v83
	v_add_f32_e64 v82, v176, v82
	v_add_f32_e64 v83, v177, v83
	v_add_f32_e64 v82, v82, v220
	v_add_f32_e64 v83, v83, v221
	v_add_f32_e32 v82, v218, v82
	v_add_f32_e32 v83, v219, v83
	v_mfma_f32_32x32x16_bf16 v[34:49], v[86:89], v[130:133], v[34:49]
	v_add_f32_e64 v82, v216, v82
	v_add_f32_e64 v83, v217, v83
	v_add_f32_e64 v82, v214, v82
	v_add_f32_e64 v83, v215, v83
	v_add_f32_e64 v82, v212, v82
	v_add_f32_e64 v83, v213, v83
	v_add_f32_e32 v82, v210, v82
	v_add_f32_e32 v83, v211, v83
	v_mfma_f32_32x32x16_bf16 v[2:17], v[90:93], v[130:133], v[2:17]
	v_add_f32_e64 v82, v208, v82
	v_add_f32_e64 v83, v209, v83
	v_add_f32_e64 v82, v206, v82
	v_add_f32_e64 v83, v207, v83
	v_add_f32_e64 v82, v204, v82
	v_add_f32_e64 v83, v205, v83
	v_add_f32_e32 v82, v202, v82
	v_add_f32_e32 v83, v203, v83
	s_nop 0
	v_add_f32_e32 v82, v200, v82
	v_add_f32_e32 v83, v201, v83
	s_nop 0
	v_add_f32_e32 v82, v198, v82
	v_add_f32_e32 v83, v199, v83
	s_nop 0
	v_add_f32_e32 v82, v196, v82
	v_add_f32_e32 v83, v197, v83
	s_nop 0
	v_add_f32_e32 v82, v194, v82
	v_add_f32_e32 v83, v195, v83
	s_nop 0
	v_add_f32_e32 v82, v192, v82
	v_add_f32_e32 v83, v193, v83
	s_nop 0
	v_add_f32_e32 v130, v190, v82
	v_add_f32_e32 v131, v191, v83
	v_add_u32_e32 v82, 0x3500, v236
	s_mov_b32 s17, s15
	s_setprio 0
	s_waitcnt vmcnt(1)
	ds_write_b128 v237, v[122:125]
	s_waitcnt vmcnt(0)
	ds_write_b128 v237, v[126:129] offset:4608
	ds_write2_b64 v238, v[118:119], v[120:121] offset1:1
	ds_write2_b64 v82, v[114:115], v[116:117] offset1:1
	s_waitcnt lgkmcnt(0)
	s_barrier
	s_cbranch_vccnz .LBB0_405
	v_and_b32_e32 v51, 64, v233
	v_xor_b32_e32 v50, 32, v233
	v_add_u32_e32 v51, 64, v51
	v_cmp_lt_i32_e32 vcc, v50, v51
	v_mov_b32_e32 v163, v139
	s_cmpk_gt_i32 s16, 0x5ff
	v_cndmask_b32_e32 v50, v233, v50, vcc
	v_lshlrev_b32_e32 v51, 2, v50
	ds_bpermute_b32 v50, v51, v130
	ds_bpermute_b32 v52, v51, v131
	s_waitcnt lgkmcnt(1)
	v_add_f32_e32 v50, v130, v50
	v_div_scale_f32 v53, s[0:1], v50, v50, 1.0
	v_rcp_f32_e32 v54, v53
	v_div_scale_f32 v55, vcc, 1.0, v50, 1.0
	s_waitcnt lgkmcnt(0)
	v_add_f32_e32 v52, v131, v52
	v_fma_f32 v56, -v53, v54, 1.0
	v_fmac_f32_e32 v54, v56, v54
	v_mul_f32_e32 v56, v55, v54
	v_fma_f32 v57, -v53, v56, v55
	v_fmac_f32_e32 v56, v57, v54
	v_fma_f32 v53, -v53, v56, v55
	v_div_scale_f32 v55, s[0:1], v52, v52, v166
	v_rcp_f32_e32 v57, v55
	v_div_fmas_f32 v53, v53, v54, v56
	v_div_fixup_f32 v50, v53, v50, 1.0
	v_fma_f32 v53, -v55, v57, 1.0
	v_fmac_f32_e32 v57, v53, v57
	v_div_scale_f32 v53, vcc, v166, v52, v166
	v_mul_f32_e32 v54, v53, v57
	v_fma_f32 v56, -v55, v54, v53
	v_fmac_f32_e32 v54, v56, v57
	v_fma_f32 v53, -v55, v54, v53
	v_div_fmas_f32 v53, v53, v57, v54
	v_div_fixup_f32 v52, v53, v52, v166
	v_mul_f32_e32 v53, v66, v52
	v_fma_f32 v53, v34, v50, -v53
	v_mul_f32_e32 v34, v67, v52
	v_fma_f32 v54, v35, v50, -v34
	v_mul_f32_e32 v34, v68, v52
	v_fma_f32 v56, v36, v50, -v34
	v_mul_f32_e32 v34, v69, v52
	v_fma_f32 v57, v37, v50, -v34
	v_mul_f32_e32 v34, v70, v52
	v_fma_f32 v38, v38, v50, -v34
	v_mul_f32_e32 v34, v71, v52
	v_fma_f32 v39, v39, v50, -v34
	v_mul_f32_e32 v34, v72, v52
	v_fma_f32 v40, v40, v50, -v34
	v_mul_f32_e32 v34, v73, v52
	v_fma_f32 v41, v41, v50, -v34
	v_mul_f32_e32 v34, v74, v52
	v_fma_f32 v42, v42, v50, -v34
	v_mul_f32_e32 v34, v75, v52
	v_fma_f32 v43, v43, v50, -v34
	v_mul_f32_e32 v34, v76, v52
	v_fma_f32 v44, v44, v50, -v34
	global_load_dwordx4 v[34:37], v[148:149], off
	v_mul_f32_e32 v55, v54, v54
	v_fmac_f32_e32 v55, v53, v53
	v_fmac_f32_e32 v55, v56, v56
	v_fmac_f32_e32 v55, v57, v57
	v_fmac_f32_e32 v55, v38, v38
	v_fmac_f32_e32 v55, v39, v39
	v_fmac_f32_e32 v55, v40, v40
	v_fmac_f32_e32 v55, v41, v41
	v_fmac_f32_e32 v55, v42, v42
	v_fmac_f32_e32 v55, v43, v43
	v_mul_f32_e32 v58, v77, v52
	v_fmac_f32_e32 v55, v44, v44
	v_fma_f32 v45, v45, v50, -v58
	v_mul_f32_e32 v58, v78, v52
; __device__ __forceinline__ ConvD conv_expert_desc(const Params& P, int l, int it) {
;   ConvD d;
;   int kind = it / 8192, r = it % 8192;
;   int e = r / 512, q = r % 512;
;   if (kind < 2) {
;     int kt = q / 32, nt = q % 32;
;     d.src = (kind == 0 ? P.w_gate : P.w_up) + ((size_t)(l * 16 + e)) * DM * 2048 + (size_t)kt * 64 * 2048 + nt * 64;
;     d.ld = 2048;
;     d.dst = WSP(u16, OFF_WGU) + (size_t)e * 4096 * DM + ((size_t)kt * 4096 + nt * 128 + (kind ? 64 : 0)) * 64;
;     d.ldd = 64;
;   } else {
;     int kt = q / 16, nt = q % 16;
;     d.src = P.w_down + ((size_t)(l * 16 + e)) * 2048 * DM + (size_t)kt * 64 * DM + nt * 64;
;     d.ld = DM;
;     d.dst = WSP(u16, OFF_WDN) + (size_t)e * DM * 2048 + ((size_t)kt * 1024 + nt * 64) * 64;
;     d.ldd = 64;
;   }
; __device__ __forceinline__ void df_block(const Params& P, int l, int b, int qrow_blk, int h, int tk_lo, int tk_hi, char* smem) {
;     ...
;   float ss = 0.f;
; #pragma unroll
;   for (int m = 0; m < 2; ++m)
; #pragma unroll
;     for (int j = 0; j < 16; ++j) {
;       float v = o1[m][j] * r1 - o2[m][j] * r2;
;       o1[m][j] = v;
;       ss += v * v;
;     }
;   ss += __shfl_xor(ss, 32);
;   const float rinv = rsqrtf(ss * (1.f / 64.f) + EPS) * (1.f - lam_init);
;   const float* sg = P.df_subln_g + l * 64;
;   u16* dst = WSP(u16, OFF_ODF) + (size_t)qrow * 384 + h * 64;
; #pragma unroll
;   for (int m = 0; m < 2; ++m)
; #pragma unroll
;     for (int g = 0; g < 4; ++g) {
;       int dv = m * 32 + 8 * g + 4 * hh;
;       uint2 w;
;       w.x = pack2(o1[m][4 * g + 0] * rinv * sg[dv + 0], o1[m][4 * g + 1] * rinv * sg[dv + 1]);
;       w.y = pack2(o1[m][4 * g + 2] * rinv * sg[dv + 2], o1[m][4 * g + 3] * rinv * sg[dv + 3]);
;       *(uint2*)(dst + dv) = w;
;     }
	v_fmac_f32_e32 v55, v45, v45
	v_fma_f32 v46, v46, v50, -v58
	v_mul_f32_e32 v58, v79, v52
	v_fmac_f32_e32 v55, v46, v46
	v_fma_f32 v47, v47, v50, -v58
	v_mul_f32_e32 v58, v80, v52
	v_fmac_f32_e32 v55, v47, v47
	v_fma_f32 v48, v48, v50, -v58
	v_mul_f32_e32 v58, v81, v52
	v_mul_f32_e32 v18, v18, v52
	v_fmac_f32_e32 v55, v48, v48
	v_fma_f32 v49, v49, v50, -v58
	v_fma_f32 v18, v2, v50, -v18
	v_mul_f32_e32 v2, v19, v52
	v_fmac_f32_e32 v55, v49, v49
	v_fma_f32 v19, v3, v50, -v2
	v_mul_f32_e32 v2, v20, v52
	v_fmac_f32_e32 v55, v18, v18
	v_fma_f32 v20, v4, v50, -v2
	v_mul_f32_e32 v2, v21, v52
	v_fmac_f32_e32 v55, v19, v19
	v_fma_f32 v21, v5, v50, -v2
	v_mul_f32_e32 v2, v22, v52
	v_fmac_f32_e32 v55, v20, v20
	v_fma_f32 v22, v6, v50, -v2
	v_mul_f32_e32 v2, v23, v52
	v_fmac_f32_e32 v55, v21, v21
	v_fma_f32 v23, v7, v50, -v2
	v_pk_mul_f32 v[2:3], v[24:25], v[52:53] op_sel_hi:[1,0]
	v_fmac_f32_e32 v55, v22, v22
	v_pk_fma_f32 v[6:7], v[8:9], v[50:51], v[2:3] op_sel_hi:[1,0,1] neg_lo:[0,0,1] neg_hi:[0,0,1]
	v_fmac_f32_e32 v55, v23, v23
	v_pk_mul_f32 v[2:3], v[6:7], v[6:7]
	s_nop 0
	v_add_f32_e32 v2, v2, v55
	v_add_f32_e32 v4, v3, v2
	v_pk_mul_f32 v[2:3], v[26:27], v[52:53] op_sel_hi:[1,0]
	s_nop 0
	v_pk_fma_f32 v[8:9], v[10:11], v[50:51], v[2:3] op_sel_hi:[1,0,1] neg_lo:[0,0,1] neg_hi:[0,0,1]
	s_nop 0
	v_pk_mul_f32 v[2:3], v[8:9], v[8:9]
	s_nop 0
	v_add_f32_e32 v2, v2, v4
	v_add_f32_e32 v4, v3, v2
	v_pk_mul_f32 v[2:3], v[28:29], v[52:53] op_sel_hi:[1,0]
	s_nop 0
	v_pk_fma_f32 v[10:11], v[12:13], v[50:51], v[2:3] op_sel_hi:[1,0,1] neg_lo:[0,0,1] neg_hi:[0,0,1]
	s_nop 0
	v_pk_mul_f32 v[2:3], v[10:11], v[10:11]
	s_nop 0
	v_add_f32_e32 v2, v2, v4
	v_add_f32_e32 v4, v3, v2
	v_pk_mul_f32 v[2:3], v[30:31], v[52:53] op_sel_hi:[1,0]
	s_nop 0
	v_pk_fma_f32 v[12:13], v[14:15], v[50:51], v[2:3] op_sel_hi:[1,0,1] neg_lo:[0,0,1] neg_hi:[0,0,1]
	s_nop 0
	v_pk_mul_f32 v[2:3], v[12:13], v[12:13]
	s_nop 0
	v_add_f32_e32 v2, v2, v4
	v_add_f32_e32 v4, v3, v2
	v_pk_mul_f32 v[2:3], v[32:33], v[52:53] op_sel_hi:[1,0]
	s_nop 0
	v_pk_fma_f32 v[14:15], v[16:17], v[50:51], v[2:3] op_sel_hi:[1,0,1] neg_lo:[0,0,1] neg_hi:[0,0,1]
	s_nop 0
	v_pk_mul_f32 v[2:3], v[14:15], v[14:15]
	s_nop 0
	v_add_f32_e32 v2, v2, v4
	v_add_f32_e32 v2, v3, v2
	ds_bpermute_b32 v3, v51, v2
	s_waitcnt lgkmcnt(0)
	v_add_f32_e32 v2, v2, v3
	v_fmamk_f32 v2, v2, 0x3c800000, v234
	v_mul_f32_e32 v3, 0x4b800000, v2
	v_cmp_gt_f32_e32 vcc, s35, v2
	s_nop 1
	v_cndmask_b32_e32 v2, v2, v3, vcc
	v_rsq_f32_e32 v2, v2
	s_nop 0
	v_mul_f32_e32 v3, 0x45800000, v2
	v_cndmask_b32_e32 v2, v2, v3, vcc
	v_sub_f32_e32 v3, 1.0, v167
	v_mul_f32_e32 v24, v3, v2
	v_mul_f32_e32 v4, v53, v24
	v_mul_f32_e32 v5, v54, v24
	s_waitcnt vmcnt(0)
	v_mul_f32_e32 v4, v34, v4
	v_mul_f32_e32 v5, v35, v5
	v_lshl_add_u64 v[2:3], s[8:9], 0, v[168:169]
	v_cvt_pk_bf16_f32 v4, v4, v5
	v_mul_f32_e32 v5, v56, v24
	v_mul_f32_e32 v16, v57, v24
	v_lshl_add_u64 v[2:3], s[12:13], 1, v[2:3]
	v_mul_f32_e32 v5, v36, v5
	v_mul_f32_e32 v16, v37, v16
	v_cvt_pk_bf16_f32 v5, v5, v16
	v_lshl_add_u64 v[16:17], v[2:3], 0, v[162:163]
	global_store_dwordx2 v[16:17], v[4:5], off
	global_load_dwordx4 v[2:5], v[148:149], off offset:32
	v_mul_f32_e32 v25, v38, v24
	v_mul_f32_e32 v26, v39, v24
	v_mul_f32_e32 v28, v41, v24
	v_mul_f32_e32 v27, v40, v24
	v_mul_f32_e32 v18, v18, v24
	v_mul_f32_e32 v19, v19, v24
	v_mul_f32_e32 v20, v20, v24
	v_mul_f32_e32 v21, v21, v24
	v_mul_f32_e32 v6, v6, v24
	v_mul_f32_e32 v7, v7, v24
	s_waitcnt vmcnt(0)
	v_mul_f32_e32 v2, v2, v25
	v_mul_f32_e32 v3, v3, v26
	v_cvt_pk_bf16_f32 v2, v2, v3
	v_mul_f32_e32 v3, v5, v28
	v_mul_f32_e32 v4, v4, v27
	v_cvt_pk_bf16_f32 v3, v4, v3
	global_store_dwordx2 v[16:17], v[2:3], off offset:16
	global_load_dwordx4 v[2:5], v[148:149], off offset:64
	v_mul_f32_e32 v25, v42, v24
	v_mul_f32_e32 v26, v43, v24
	v_mul_f32_e32 v27, v44, v24
	v_mul_f32_e32 v28, v45, v24
	s_waitcnt vmcnt(0)
	v_mul_f32_e32 v2, v2, v25
	v_mul_f32_e32 v3, v3, v26
	v_mul_f32_e32 v4, v4, v27
	v_mul_f32_e32 v5, v5, v28
	v_cvt_pk_bf16_f32 v2, v2, v3
	v_cvt_pk_bf16_f32 v3, v4, v5
	global_store_dwordx2 v[16:17], v[2:3], off offset:32
	global_load_dwordx4 v[2:5], v[148:149], off offset:96
	v_mul_f32_e32 v25, v46, v24
	v_mul_f32_e32 v26, v47, v24
	v_mul_f32_e32 v27, v48, v24
	v_mul_f32_e32 v28, v49, v24
	s_waitcnt vmcnt(0)
	v_mul_f32_e32 v2, v2, v25
	v_mul_f32_e32 v3, v3, v26
	v_mul_f32_e32 v4, v4, v27
	v_mul_f32_e32 v5, v5, v28
	v_cvt_pk_bf16_f32 v2, v2, v3
	v_cvt_pk_bf16_f32 v3, v4, v5
	global_store_dwordx2 v[16:17], v[2:3], off offset:48
	global_load_dwordx4 v[2:5], v[148:149], off offset:128
	s_waitcnt vmcnt(0)
	v_mul_f32_e32 v2, v2, v18
	v_mul_f32_e32 v3, v3, v19
	v_mul_f32_e32 v4, v4, v20
	v_mul_f32_e32 v5, v5, v21
	v_cvt_pk_bf16_f32 v2, v2, v3
	v_cvt_pk_bf16_f32 v3, v4, v5
	global_store_dwordx2 v[16:17], v[2:3], off offset:64
	global_load_dwordx4 v[2:5], v[148:149], off offset:160
	v_mul_f32_e32 v18, v22, v24
	v_mul_f32_e32 v19, v23, v24
	s_waitcnt vmcnt(0)
	v_mul_f32_e32 v2, v2, v18
	v_mul_f32_e32 v3, v3, v19
	v_mul_f32_e32 v4, v4, v6
	v_mul_f32_e32 v5, v5, v7
	v_cvt_pk_bf16_f32 v2, v2, v3
	v_cvt_pk_bf16_f32 v3, v4, v5
	global_store_dwordx2 v[16:17], v[2:3], off offset:80
	global_load_dwordx4 v[2:5], v[148:149], off offset:192
	v_mul_f32_e32 v6, v8, v24
	v_mul_f32_e32 v7, v9, v24
	v_mul_f32_e32 v8, v10, v24
	v_mul_f32_e32 v9, v11, v24
	s_waitcnt vmcnt(0)
	v_mul_f32_e32 v2, v6, v2
	v_mul_f32_e32 v3, v7, v3
	v_mul_f32_e32 v4, v8, v4
	v_mul_f32_e32 v5, v9, v5
	v_cvt_pk_bf16_f32 v2, v2, v3
	v_cvt_pk_bf16_f32 v3, v4, v5
	global_store_dwordx2 v[16:17], v[2:3], off offset:96
	global_load_dwordx4 v[2:5], v[148:149], off offset:224
	v_mul_f32_e32 v6, v12, v24
	v_mul_f32_e32 v7, v13, v24
	v_mul_f32_e32 v8, v14, v24
	v_mul_f32_e32 v9, v15, v24
	s_waitcnt vmcnt(0)
	v_mul_f32_e32 v2, v6, v2
	v_mul_f32_e32 v3, v7, v3
	v_mul_f32_e32 v4, v8, v4
	v_mul_f32_e32 v5, v9, v5
	v_cvt_pk_bf16_f32 v2, v2, v3
	v_cvt_pk_bf16_f32 v3, v4, v5
	global_store_dwordx2 v[16:17], v[2:3], off offset:112
	s_cbranch_scc1 .LBB0_419
	s_bfe_i32 s0, s16, 0x1001b
	s_lshl_b32 s36, s16, 4
	s_lshr_b32 s0, s0, 19
	s_add_i32 s0, s36, s0
	s_and_b32 s0, s0, 0xffffe000
	s_sub_i32 s0, s36, s0
	s_sext_i32_i16 s1, s0
	s_bfe_u32 s1, s1, 0x90016
	s_add_i32 s1, s0, s1
	s_sext_i32_i16 s10, s1
	s_and_b32 s1, s1, 0xfe00
	s_lshr_b32 s18, s10, 9
	s_sub_i32 s19, s0, s1
	s_cmpk_gt_i32 s16, 0x3ff
	s_mov_b64 s[16:17], -1
	s_cbranch_scc0 .LBB0_409
	s_and_b32 s10, s18, 0xffff
	s_and_b32 s16, 0xffff, s19
	s_lshl_b64 s[0:1], s[10:11], 23
	s_add_u32 s0, s54, s0
	s_addc_u32 s1, s55, s1
	s_lshl_b32 s12, s16, 14
	s_add_u32 s0, s0, s12
	s_addc_u32 s1, s1, 0
	s_lshl_b32 s12, s16, 6
	s_and_b32 s14, s12, 0x3c0
	s_lshl_b32 s12, s14, 2
	s_add_u32 s0, s0, s12
	s_addc_u32 s1, s1, 0
	s_lshl_b64 s[12:13], s[10:11], 22
	s_and_b32 s10, s13, 1
	s_add_u32 s12, s25, s12
	s_addc_u32 s10, s26, s10
	s_lshl_b32 s13, s16, 13
	s_add_u32 s12, s12, s13
	s_mov_b32 s15, s11
	s_addc_u32 s13, s10, 0
	s_mov_b64 s[16:17], 0

; __device__ __forceinline__ float fast_exp2(float x) { return __builtin_amdgcn_exp2f(x); }
; __device__ __forceinline__ void df_block(const Params& P, int l, int b, int qrow_blk, int h, int tk_lo, int tk_hi, char* smem) {
;     ...
;   for (int tk = tk_lo; tk < tk_hi; tk += 64) {
;     const int tn = (tk + 64 < tk_hi) ? tk + 64 : tk;
;     rk0 = *(const uint4*)(KD + (size_t)key_row(b, tn + lrow0) * 384 + h * 64 + lch * 8);
;     rk1 = *(const uint4*)(KD + (size_t)key_row(b, tn + lrow0 + 32) * 384 + h * 64 + lch * 8);
;     rv0 = *(const uint4*)(vsrc0 + tn);
;     rv1 = *(const uint4*)(vsrc1 + tn);
;     __builtin_amdgcn_sched_barrier(0);
;     const char* Ks = smem + cur * DF_BUF;
;     const char* Vs = Ks + DF_KBYTES;
; #pragma unroll
;     for (int sub = 0; sub < 2; ++sub) {
;       const char* kp = Ks + (sub * 32 + ql) * DF_KSTR + hh * 16;
;       bf16x8 pa0, pa1, pb0, pb1;
;       {
;         f32x16 S = mfma32(*(const bf16x8*)(kp), q1[0], cini);
;         S = mfma32(*(const bf16x8*)(kp + 32), q1[1], S);
;         float p[16];
; #pragma unroll
;         for (int j = 0; j < 16; ++j) { p[j] = fast_exp2(S[j]); l1 += p[j]; }
;         pack_p(p, pa0, pa1);
;       }
;       {
;         f32x16 S = mfma32(*(const bf16x8*)(kp + 64), q2[0], cini);
;         S = mfma32(*(const bf16x8*)(kp + 96), q2[1], S);
;         float p[16];
; #pragma unroll
;         for (int j = 0; j < 16; ++j) { p[j] = fast_exp2(S[j]); l2 += p[j]; }
;         pack_p(p, pb0, pb1);
;       }
; #pragma unroll
;       for (int s2 = 0; s2 < 2; ++s2) {
;         const char* vp0 = Vs + ql * DF_VSTR + (sub * 32 + 16 * s2 + 4 * hh) * 2;
;         const char* vp1 = vp0 + 32 * DF_VSTR;
;         union { uint4 u; bf16x8 v; } c0, c1;
;         uint2 a0 = *(const uint2*)(vp0), a1 = *(const uint2*)(vp0 + 16);
;         uint2 e0 = *(const uint2*)(vp1), e1 = *(const uint2*)(vp1 + 16);
;         c0.u = make_uint4(a0.x, a0.y, a1.x, a1.y);
;         c1.u = make_uint4(e0.x, e0.y, e1.x, e1.y);
;         o1[0] = mfma32(c0.v, s2 ? pa1 : pa0, o1[0]);
;         o1[1] = mfma32(c1.v, s2 ? pa1 : pa0, o1[1]);
;         o2[0] = mfma32(c0.v, s2 ? pb1 : pb0, o2[0]);
;         o2[1] = mfma32(c1.v, s2 ? pb1 : pb0, o2[1]);
;       }
;     }
.LBB0_1434:
	s_add_i32 s18, s0, 64
	s_cmpk_lt_u32 s0, 0x10c0
	s_cselect_b64 s[20:21], -1, 0
	s_and_b64 vcc, s[20:21], exec
	s_cselect_b32 s12, s18, s0
	v_add_u32_e32 v86, s12, v135
	v_cmp_gt_u32_e64 s[0:1], s31, v86
	s_lshl_b64 s[20:21], s[12:13], 1
	v_lshl_add_u64 v[82:83], v[170:171], 0, s[20:21]
	v_cndmask_b32_e64 v87, v163, v140, s[0:1]
	v_cmp_gt_u32_e64 s[0:1], s34, v86
	v_add_u32_e32 v87, v87, v86
	v_lshl_add_u64 v[84:85], v[172:173], 0, s[20:21]
	v_cndmask_b32_e64 v88, v165, v235, s[0:1]
	v_add_u32_e32 v86, v88, v86
	global_load_dwordx4 v[118:121], v[82:83], off
	global_load_dwordx4 v[114:117], v[84:85], off
	v_mad_i64_i32 v[82:83], s[0:1], v87, s29, v[174:175]
	v_mad_i64_i32 v[84:85], s[0:1], v86, s29, v[174:175]
	global_load_dwordx4 v[122:125], v[82:83], off
	global_load_dwordx4 v[126:129], v[84:85], off
	s_mul_i32 s0, s17, 0x4600
	s_xor_b32 s17, s17, 1
	v_or_b32_e32 v82, s0, v142
	v_add3_u32 v218, s0, v139, v138
	s_mul_i32 s0, s17, 0x4600
	v_add_u32_e32 v236, s0, v143
	v_add_u32_e32 v219, v82, v145
	v_add_u32_e32 v237, s0, v137
	v_add_u32_e32 v238, 0x2400, v236
	s_setprio 1
	ds_read_b128 v[176:179], v219
	ds_read_b128 v[180:183], v219 offset:32
	ds_read_b128 v[196:199], v219 offset:64
	v_add_u32_e32 v239, 0x2000, v218
	v_add_u32_e32 v248, 0x3000, v218
	s_waitcnt vmcnt(7) lgkmcnt(2)
	v_mfma_f32_32x32x16_bf16 v[82:97], v[176:179], v[98:101], v[66:81]
	s_waitcnt vmcnt(4) lgkmcnt(1)
	v_mfma_f32_32x32x16_bf16 v[82:97], v[180:183], v[110:113], v[82:97]
	s_nop 11
	v_exp_f32_e32 v132, v82
	v_exp_f32_e32 v200, v83
	v_exp_f32_e32 v202, v84
	v_exp_f32_e32 v204, v85
	v_exp_f32_e32 v206, v86
	v_exp_f32_e32 v208, v87
	v_exp_f32_e32 v210, v88
	v_exp_f32_e32 v212, v89
	v_exp_f32_e32 v214, v90
	v_exp_f32_e32 v216, v91
	v_exp_f32_e32 v186, v92
	v_exp_f32_e32 v184, v93
	v_exp_f32_e32 v182, v94
	v_exp_f32_e32 v180, v95
	v_exp_f32_e32 v178, v96
	v_exp_f32_e32 v176, v97
	s_waitcnt lgkmcnt(0)
	v_mfma_f32_32x32x16_bf16 v[82:97], v[196:199], v[106:109], v[66:81]
	ds_read_b128 v[196:199], v219 offset:96
	v_cvt_pk_bf16_f32 v188, v132, v200
	v_cvt_pk_bf16_f32 v189, v202, v204
	v_cvt_pk_bf16_f32 v190, v206, v208
	v_cvt_pk_bf16_f32 v191, v210, v212
	v_cvt_pk_bf16_f32 v192, v214, v216
	v_cvt_pk_bf16_f32 v193, v186, v184
	s_waitcnt lgkmcnt(0)
	v_mfma_f32_32x32x16_bf16 v[82:97], v[196:199], v[102:105], v[82:97]
	v_cvt_pk_bf16_f32 v194, v182, v180
	v_cvt_pk_bf16_f32 v195, v178, v176
	s_nop 11
	v_exp_f32_e32 v215, v90
	v_exp_f32_e32 v217, v91
	v_exp_f32_e32 v187, v92
	v_exp_f32_e32 v185, v93
	v_exp_f32_e32 v183, v94
	v_exp_f32_e32 v181, v95
	v_exp_f32_e32 v179, v96
	v_exp_f32_e32 v177, v97
	ds_read2_b64 v[90:93], v239 offset0:128 offset1:130
	ds_read2_b64 v[94:97], v239 offset0:132 offset1:134
	ds_read2_b64 v[196:199], v248 offset0:160 offset1:162
	v_exp_f32_e32 v133, v82
	v_exp_f32_e32 v201, v83
	v_exp_f32_e32 v203, v84
	v_exp_f32_e32 v205, v85
	v_exp_f32_e32 v207, v86
	v_exp_f32_e32 v209, v87
	v_exp_f32_e32 v211, v88
	v_exp_f32_e32 v213, v89
	v_cvt_pk_bf16_f32 v82, v133, v201
	v_cvt_pk_bf16_f32 v83, v203, v205
	v_cvt_pk_bf16_f32 v84, v207, v209
	v_cvt_pk_bf16_f32 v85, v211, v213
	s_waitcnt lgkmcnt(0)
	v_mfma_f32_32x32x16_bf16 v[2:17], v[196:199], v[188:191], v[2:17]
	v_cvt_pk_bf16_f32 v86, v215, v217
	v_cvt_pk_bf16_f32 v87, v187, v185
	v_cvt_pk_bf16_f32 v88, v183, v181
	v_cvt_pk_bf16_f32 v89, v179, v177
	ds_read_b128 v[244:247], v219 offset:4672
	v_mfma_f32_32x32x16_bf16 v[50:65], v[90:93], v[82:85], v[50:65]
	v_mfma_f32_32x32x16_bf16 v[18:33], v[196:199], v[82:85], v[18:33]
	ds_read2_b64 v[82:85], v248 offset0:164 offset1:166
	s_waitcnt lgkmcnt(0)
	v_mfma_f32_32x32x16_bf16 v[2:17], v[82:85], v[192:195], v[2:17]
	v_mfma_f32_32x32x16_bf16 v[18:33], v[82:85], v[86:89], v[18:33]
	v_add_f32_e64 v82, v130, v132
	v_add_f32_e64 v83, v131, v133
	ds_read_b128 v[130:133], v219 offset:4608
	v_add_f32_e64 v82, v200, v82
	v_add_f32_e64 v83, v201, v83
	v_add_f32_e32 v82, v202, v82
	v_add_f32_e32 v83, v203, v83
	s_nop 0
	v_add_f32_e32 v82, v204, v82
	v_add_f32_e32 v83, v205, v83
	v_mfma_f32_32x32x16_bf16 v[34:49], v[90:93], v[188:191], v[34:49]
	v_add_f32_e64 v82, v206, v82
	v_add_f32_e64 v83, v207, v83
	v_add_f32_e64 v82, v208, v82
	v_add_f32_e64 v83, v209, v83
	v_add_f32_e64 v82, v210, v82
	v_add_f32_e64 v83, v211, v83
	v_add_f32_e32 v82, v212, v82
	v_add_f32_e32 v83, v213, v83
	v_mfma_f32_32x32x16_bf16 v[34:49], v[94:97], v[192:195], v[34:49]
	v_add_f32_e64 v82, v214, v82
	v_add_f32_e64 v83, v215, v83
	v_add_f32_e64 v188, v216, v82
	v_add_f32_e64 v189, v217, v83
	v_mfma_f32_32x32x16_bf16 v[50:65], v[94:97], v[86:89], v[50:65]
	s_waitcnt lgkmcnt(0)
	v_mfma_f32_32x32x16_bf16 v[82:97], v[130:133], v[98:101], v[66:81]
	ds_read_b128 v[130:133], v219 offset:4640
	s_waitcnt lgkmcnt(0)
	v_mfma_f32_32x32x16_bf16 v[82:97], v[130:133], v[110:113], v[82:97]
	s_nop 11
	v_exp_f32_e32 v220, v82
	v_exp_f32_e32 v218, v83
	v_exp_f32_e32 v216, v84
	v_exp_f32_e32 v214, v85
	v_exp_f32_e32 v212, v86
	v_exp_f32_e32 v210, v87
	v_exp_f32_e32 v208, v88
	v_exp_f32_e32 v206, v89
	v_exp_f32_e32 v204, v90
	v_exp_f32_e32 v202, v91
	v_exp_f32_e32 v200, v92
	v_exp_f32_e32 v198, v93
	v_exp_f32_e32 v196, v94
	v_exp_f32_e32 v194, v95
	v_exp_f32_e32 v192, v96
	v_exp_f32_e32 v190, v97
	v_mfma_f32_32x32x16_bf16 v[82:97], v[244:247], v[106:109], v[66:81]
	ds_read_b128 v[244:247], v219 offset:4704
	v_cvt_pk_bf16_f32 v240, v220, v218
	v_cvt_pk_bf16_f32 v241, v216, v214
	v_cvt_pk_bf16_f32 v242, v212, v210
	v_cvt_pk_bf16_f32 v243, v208, v206
	v_cvt_pk_bf16_f32 v130, v204, v202
	v_cvt_pk_bf16_f32 v131, v200, v198
	s_waitcnt lgkmcnt(0)
; __device__ __forceinline__ float fast_exp2(float x) { return __builtin_amdgcn_exp2f(x); }
; __device__ __forceinline__ void df_block(const Params& P, int l, int b, int qrow_blk, int h, int tk_lo, int tk_hi, char* smem) {
;     ...
;         S = mfma32(*(const bf16x8*)(kp + 96), q2[1], S);
;         float p[16];
; #pragma unroll
;         for (int j = 0; j < 16; ++j) { p[j] = fast_exp2(S[j]); l2 += p[j]; }
;         pack_p(p, pb0, pb1);
;       }
; #pragma unroll
;       for (int s2 = 0; s2 < 2; ++s2) {
;         const char* vp0 = Vs + ql * DF_VSTR + (sub * 32 + 16 * s2 + 4 * hh) * 2;
;         const char* vp1 = vp0 + 32 * DF_VSTR;
;         union { uint4 u; bf16x8 v; } c0, c1;
;         uint2 a0 = *(const uint2*)(vp0), a1 = *(const uint2*)(vp0 + 16);
;         uint2 e0 = *(const uint2*)(vp1), e1 = *(const uint2*)(vp1 + 16);
;         c0.u = make_uint4(a0.x, a0.y, a1.x, a1.y);
;         c1.u = make_uint4(e0.x, e0.y, e1.x, e1.y);
;         o1[0] = mfma32(c0.v, s2 ? pa1 : pa0, o1[0]);
;         o1[1] = mfma32(c1.v, s2 ? pa1 : pa0, o1[1]);
;         o2[0] = mfma32(c0.v, s2 ? pb1 : pb0, o2[0]);
;         o2[1] = mfma32(c1.v, s2 ? pb1 : pb0, o2[1]);
;       }
;     }
;     __builtin_amdgcn_sched_barrier(0);
;     {
;       char* d = smem + (cur ^ 1) * DF_BUF;
;       *(uint4*)(d + koff0) = rk0;
;       *(uint4*)(d + koff1) = rk1;
;       *(uint2*)(d + voff0) = make_uint2(rv0.x, rv0.y); *(uint2*)(d + voff0 + 8) = make_uint2(rv0.z, rv0.w);
;       *(uint2*)(d + voff1) = make_uint2(rv1.x, rv1.y); *(uint2*)(d + voff1 + 8) = make_uint2(rv1.z, rv1.w);
;     }
;     __syncthreads();
;     cur ^= 1;
;   }
;   l1 += __shfl_xor(l1, 32);
;   l2 += __shfl_xor(l2, 32);
;   const float r1 = 1.f / l1, r2 = lam / l2;
;   float ss = 0.f;
; #pragma unroll
;   for (int m = 0; m < 2; ++m)
; #pragma unroll
;     for (int j = 0; j < 16; ++j) {
;       float v = o1[m][j] * r1 - o2[m][j] * r2;
;       o1[m][j] = v;
;       ss += v * v;
;     }
;   ss += __shfl_xor(ss, 32);
;   const float rinv = rsqrtf(ss * (1.f / 64.f) + EPS) * (1.f - lam_init);
	v_mfma_f32_32x32x16_bf16 v[82:97], v[244:247], v[102:105], v[82:97]
	v_cvt_pk_bf16_f32 v132, v196, v194
	v_cvt_pk_bf16_f32 v133, v192, v190
	s_nop 11
	v_exp_f32_e32 v205, v90
	v_exp_f32_e32 v203, v91
	v_exp_f32_e32 v201, v92
	v_exp_f32_e32 v199, v93
	v_exp_f32_e32 v197, v94
	v_exp_f32_e32 v195, v95
	v_exp_f32_e32 v193, v96
	v_exp_f32_e32 v191, v97
	ds_read2_b64 v[90:93], v239 offset0:136 offset1:138
	ds_read2_b64 v[94:97], v248 offset0:168 offset1:170
	v_exp_f32_e32 v221, v82
	v_exp_f32_e32 v219, v83
	v_exp_f32_e32 v217, v84
	v_exp_f32_e32 v215, v85
	v_exp_f32_e32 v213, v86
	v_exp_f32_e32 v211, v87
	v_exp_f32_e32 v209, v88
	v_exp_f32_e32 v207, v89
	v_cvt_pk_bf16_f32 v86, v221, v219
	v_cvt_pk_bf16_f32 v87, v217, v215
	v_cvt_pk_bf16_f32 v88, v213, v211
	v_cvt_pk_bf16_f32 v89, v209, v207
	s_waitcnt lgkmcnt(1)
	v_mfma_f32_32x32x16_bf16 v[34:49], v[90:93], v[240:243], v[34:49]
	v_cvt_pk_bf16_f32 v82, v205, v203
	v_cvt_pk_bf16_f32 v83, v201, v199
	v_cvt_pk_bf16_f32 v84, v197, v195
	v_cvt_pk_bf16_f32 v85, v193, v191
	v_mfma_f32_32x32x16_bf16 v[50:65], v[90:93], v[86:89], v[50:65]
	s_waitcnt lgkmcnt(0)
	v_mfma_f32_32x32x16_bf16 v[18:33], v[94:97], v[86:89], v[18:33]
	ds_read2_b64 v[86:89], v239 offset0:140 offset1:142
	ds_read2_b64 v[90:93], v248 offset0:172 offset1:174
	s_waitcnt lgkmcnt(1)
	v_mfma_f32_32x32x16_bf16 v[50:65], v[86:89], v[82:85], v[50:65]
	s_waitcnt lgkmcnt(0)
	v_mfma_f32_32x32x16_bf16 v[18:33], v[90:93], v[82:85], v[18:33]
	v_add_f32_e64 v82, v186, v188
	v_add_f32_e64 v83, v187, v189
	v_add_f32_e64 v82, v184, v82
	v_add_f32_e64 v83, v185, v83
	v_add_f32_e64 v82, v182, v82
	v_add_f32_e64 v83, v183, v83
	v_add_f32_e32 v82, v180, v82
	v_add_f32_e32 v83, v181, v83
	v_mfma_f32_32x32x16_bf16 v[2:17], v[94:97], v[240:243], v[2:17]
	v_add_f32_e64 v82, v178, v82
	v_add_f32_e64 v83, v179, v83
	v_add_f32_e64 v82, v176, v82
	v_add_f32_e64 v83, v177, v83
	v_add_f32_e64 v82, v82, v220
	v_add_f32_e64 v83, v83, v221
	v_add_f32_e32 v82, v218, v82
	v_add_f32_e32 v83, v219, v83
	v_mfma_f32_32x32x16_bf16 v[34:49], v[86:89], v[130:133], v[34:49]
	v_add_f32_e64 v82, v216, v82
	v_add_f32_e64 v83, v217, v83
	v_add_f32_e64 v82, v214, v82
	v_add_f32_e64 v83, v215, v83
	v_add_f32_e64 v82, v212, v82
	v_add_f32_e64 v83, v213, v83
	v_add_f32_e32 v82, v210, v82
	v_add_f32_e32 v83, v211, v83
	v_mfma_f32_32x32x16_bf16 v[2:17], v[90:93], v[130:133], v[2:17]
	v_add_f32_e64 v82, v208, v82
	v_add_f32_e64 v83, v209, v83
	v_add_f32_e64 v82, v206, v82
	v_add_f32_e64 v83, v207, v83
	v_add_f32_e64 v82, v204, v82
	v_add_f32_e64 v83, v205, v83
	v_add_f32_e32 v82, v202, v82
	v_add_f32_e32 v83, v203, v83
	s_nop 0
	v_add_f32_e32 v82, v200, v82
	v_add_f32_e32 v83, v201, v83
	s_nop 0
	v_add_f32_e32 v82, v198, v82
	v_add_f32_e32 v83, v199, v83
	s_nop 0
	v_add_f32_e32 v82, v196, v82
	v_add_f32_e32 v83, v197, v83
	s_nop 0
	v_add_f32_e32 v82, v194, v82
	v_add_f32_e32 v83, v195, v83
	s_nop 0
	v_add_f32_e32 v82, v192, v82
	v_add_f32_e32 v83, v193, v83
	s_nop 0
	v_add_f32_e32 v130, v190, v82
	v_add_f32_e32 v131, v191, v83
	v_add_u32_e32 v82, 0x3500, v236
	s_mov_b32 s0, s18
	s_setprio 0
	s_waitcnt vmcnt(1)
	ds_write_b128 v237, v[122:125]
	s_waitcnt vmcnt(0)
	ds_write_b128 v237, v[126:129] offset:4608
	ds_write2_b64 v238, v[118:119], v[120:121] offset1:1
	ds_write2_b64 v82, v[114:115], v[116:117] offset1:1
	s_waitcnt lgkmcnt(0)
	s_barrier
	s_cbranch_vccnz .LBB0_1434
	v_and_b32_e32 v67, 64, v233
	v_xor_b32_e32 v66, 32, v233
	v_add_u32_e32 v67, 64, v67
	v_cmp_lt_i32_e32 vcc, v66, v67
	v_mov_b32_e32 v163, v141
	s_lshl_b32 s33, s16, 4
	v_cndmask_b32_e32 v66, v233, v66, vcc
	v_lshlrev_b32_e32 v67, 2, v66
	ds_bpermute_b32 v66, v67, v130
	ds_bpermute_b32 v68, v67, v131
	s_mov_b64 s[20:21], -1
	s_waitcnt lgkmcnt(1)
	v_add_f32_e32 v66, v130, v66
	v_div_scale_f32 v69, s[0:1], v66, v66, 1.0
	v_rcp_f32_e32 v70, v69
	v_div_scale_f32 v71, vcc, 1.0, v66, 1.0
	s_waitcnt lgkmcnt(0)
	v_add_f32_e32 v68, v131, v68
	v_fma_f32 v72, -v69, v70, 1.0
	v_fmac_f32_e32 v70, v72, v70
	v_mul_f32_e32 v72, v71, v70
	v_fma_f32 v73, -v69, v72, v71
	v_fmac_f32_e32 v72, v73, v70
	v_fma_f32 v69, -v69, v72, v71
	v_div_scale_f32 v71, s[0:1], v68, v68, v166
	v_rcp_f32_e32 v73, v71
	v_div_fmas_f32 v69, v69, v70, v72
	v_div_fixup_f32 v66, v69, v66, 1.0
	s_bfe_i32 s0, s16, 0x1001b
	v_fma_f32 v69, -v71, v73, 1.0
	v_fmac_f32_e32 v73, v69, v73
	v_div_scale_f32 v69, vcc, v166, v68, v166
	v_mul_f32_e32 v70, v69, v73
	v_fma_f32 v72, -v71, v70, v69
	v_fmac_f32_e32 v70, v72, v73
	v_fma_f32 v69, -v71, v70, v69
	v_div_fmas_f32 v69, v69, v73, v70
	v_div_fixup_f32 v68, v69, v68, v166
	v_mul_f32_e32 v50, v50, v68
	v_fma_f32 v50, v34, v66, -v50
	v_mul_f32_e32 v34, v51, v68
	v_fma_f32 v51, v35, v66, -v34
	v_mul_f32_e32 v34, v52, v68
	v_fma_f32 v52, v36, v66, -v34
	v_mul_f32_e32 v34, v53, v68
	v_fma_f32 v53, v37, v66, -v34
	v_mul_f32_e32 v34, v54, v68
	v_fma_f32 v38, v38, v66, -v34
	v_mul_f32_e32 v34, v55, v68
	v_fma_f32 v39, v39, v66, -v34
	v_mul_f32_e32 v34, v56, v68
	v_fma_f32 v40, v40, v66, -v34
	v_mul_f32_e32 v34, v57, v68
	v_fma_f32 v41, v41, v66, -v34
	v_mul_f32_e32 v34, v58, v68
	v_fma_f32 v42, v42, v66, -v34
	v_mul_f32_e32 v34, v59, v68
	v_fma_f32 v43, v43, v66, -v34
	v_mul_f32_e32 v34, v60, v68
	v_fma_f32 v44, v44, v66, -v34
	global_load_dwordx4 v[34:37], v[150:151], off offset:256
	v_mul_f32_e32 v69, v51, v51
	v_fmac_f32_e32 v69, v50, v50
	v_fmac_f32_e32 v69, v52, v52
	v_fmac_f32_e32 v69, v53, v53
	v_fmac_f32_e32 v69, v38, v38
	v_fmac_f32_e32 v69, v39, v39
	v_fmac_f32_e32 v69, v40, v40
	v_fmac_f32_e32 v69, v41, v41
	v_fmac_f32_e32 v69, v42, v42
	v_fmac_f32_e32 v69, v43, v43
	v_mul_f32_e32 v54, v61, v68
	v_fmac_f32_e32 v69, v44, v44
; __device__ __forceinline__ ConvD conv_expert_desc(const Params& P, int l, int it) {
;   ConvD d;
;   int kind = it / 8192, r = it % 8192;
;   int e = r / 512, q = r % 512;
;   if (kind < 2) {
;     int kt = q / 32, nt = q % 32;
;     d.src = (kind == 0 ? P.w_gate : P.w_up) + ((size_t)(l * 16 + e)) * DM * 2048 + (size_t)kt * 64 * 2048 + nt * 64;
;     d.ld = 2048;
;     d.dst = WSP(u16, OFF_WGU) + (size_t)e * 4096 * DM + ((size_t)kt * 4096 + nt * 128 + (kind ? 64 : 0)) * 64;
;     d.ldd = 64;
;   } else {
;     int kt = q / 16, nt = q % 16;
;     d.src = P.w_down + ((size_t)(l * 16 + e)) * 2048 * DM + (size_t)kt * 64 * DM + nt * 64;
;     d.ld = DM;
;     d.dst = WSP(u16, OFF_WDN) + (size_t)e * DM * 2048 + ((size_t)kt * 1024 + nt * 64) * 64;
;     d.ldd = 64;
;   }
; __device__ __forceinline__ void df_block(const Params& P, int l, int b, int qrow_blk, int h, int tk_lo, int tk_hi, char* smem) {
;     ...
;   float ss = 0.f;
; #pragma unroll
;   for (int m = 0; m < 2; ++m)
; #pragma unroll
;     for (int j = 0; j < 16; ++j) {
;       float v = o1[m][j] * r1 - o2[m][j] * r2;
;       o1[m][j] = v;
;       ss += v * v;
;     }
;   ss += __shfl_xor(ss, 32);
;   const float rinv = rsqrtf(ss * (1.f / 64.f) + EPS) * (1.f - lam_init);
;   const float* sg = P.df_subln_g + l * 64;
;   u16* dst = WSP(u16, OFF_ODF) + (size_t)qrow * 384 + h * 64;
; #pragma unroll
;   for (int m = 0; m < 2; ++m)
; #pragma unroll
;     for (int g = 0; g < 4; ++g) {
;       int dv = m * 32 + 8 * g + 4 * hh;
;       uint2 w;
;       w.x = pack2(o1[m][4 * g + 0] * rinv * sg[dv + 0], o1[m][4 * g + 1] * rinv * sg[dv + 1]);
;       w.y = pack2(o1[m][4 * g + 2] * rinv * sg[dv + 2], o1[m][4 * g + 3] * rinv * sg[dv + 3]);
;       *(uint2*)(dst + dv) = w;
;     }
	v_fma_f32 v45, v45, v66, -v54
	v_mul_f32_e32 v54, v62, v68
	v_fmac_f32_e32 v69, v45, v45
	v_fma_f32 v46, v46, v66, -v54
	v_mul_f32_e32 v54, v63, v68
	v_fmac_f32_e32 v69, v46, v46
	v_fma_f32 v47, v47, v66, -v54
	v_mul_f32_e32 v54, v64, v68
	v_fmac_f32_e32 v69, v47, v47
	v_fma_f32 v48, v48, v66, -v54
	v_mul_f32_e32 v54, v65, v68
	v_fmac_f32_e32 v69, v48, v48
	v_fma_f32 v49, v49, v66, -v54
	v_mul_f32_e32 v18, v18, v68
	v_fmac_f32_e32 v69, v49, v49
	v_fma_f32 v18, v2, v66, -v18
	v_mul_f32_e32 v2, v19, v68
	v_fmac_f32_e32 v69, v18, v18
	v_fma_f32 v19, v3, v66, -v2
	v_mul_f32_e32 v2, v20, v68
	v_fmac_f32_e32 v69, v19, v19
	v_fma_f32 v20, v4, v66, -v2
	v_mul_f32_e32 v2, v21, v68
	v_fmac_f32_e32 v69, v20, v20
	v_fma_f32 v21, v5, v66, -v2
	v_mul_f32_e32 v2, v22, v68
	v_fmac_f32_e32 v69, v21, v21
	v_fma_f32 v22, v6, v66, -v2
	v_mul_f32_e32 v2, v23, v68
	v_fmac_f32_e32 v69, v22, v22
	v_fma_f32 v23, v7, v66, -v2
	v_fmac_f32_e32 v69, v23, v23
	v_pk_mul_f32 v[2:3], v[24:25], v[68:69] op_sel_hi:[1,0]
	s_lshr_b32 s0, s0, 19
	v_pk_fma_f32 v[6:7], v[8:9], v[66:67], v[2:3] op_sel_hi:[1,0,1] neg_lo:[0,0,1] neg_hi:[0,0,1]
	s_add_i32 s0, s33, s0
	v_pk_mul_f32 v[2:3], v[6:7], v[6:7]
	s_and_b32 s0, s0, 0xffffe000
	v_add_f32_e32 v2, v2, v69
	v_add_f32_e32 v4, v3, v2
	v_pk_mul_f32 v[2:3], v[26:27], v[68:69] op_sel_hi:[1,0]
	s_sub_i32 s1, s33, s0
	v_pk_fma_f32 v[8:9], v[10:11], v[66:67], v[2:3] op_sel_hi:[1,0,1] neg_lo:[0,0,1] neg_hi:[0,0,1]
	s_sext_i32_i16 s0, s1
	v_pk_mul_f32 v[2:3], v[8:9], v[8:9]
	s_bfe_u32 s0, s0, 0x90016
	v_add_f32_e32 v2, v2, v4
	v_add_f32_e32 v4, v3, v2
	v_pk_mul_f32 v[2:3], v[28:29], v[68:69] op_sel_hi:[1,0]
	s_add_i32 s0, s1, s0
	v_pk_fma_f32 v[10:11], v[12:13], v[66:67], v[2:3] op_sel_hi:[1,0,1] neg_lo:[0,0,1] neg_hi:[0,0,1]
	s_sext_i32_i16 s12, s0
	v_pk_mul_f32 v[2:3], v[10:11], v[10:11]
	s_nop 0
	v_add_f32_e32 v2, v2, v4
	v_add_f32_e32 v4, v3, v2
	v_pk_mul_f32 v[2:3], v[30:31], v[68:69] op_sel_hi:[1,0]
	s_nop 0
	v_pk_fma_f32 v[12:13], v[14:15], v[66:67], v[2:3] op_sel_hi:[1,0,1] neg_lo:[0,0,1] neg_hi:[0,0,1]
	s_nop 0
	v_pk_mul_f32 v[2:3], v[12:13], v[12:13]
	s_nop 0
	v_add_f32_e32 v2, v2, v4
	v_add_f32_e32 v4, v3, v2
	v_pk_mul_f32 v[2:3], v[32:33], v[68:69] op_sel_hi:[1,0]
	s_nop 0
	v_pk_fma_f32 v[14:15], v[16:17], v[66:67], v[2:3] op_sel_hi:[1,0,1] neg_lo:[0,0,1] neg_hi:[0,0,1]
	s_nop 0
	v_pk_mul_f32 v[2:3], v[14:15], v[14:15]
	s_nop 0
	v_add_f32_e32 v2, v2, v4
	v_add_f32_e32 v2, v3, v2
	ds_bpermute_b32 v3, v67, v2
	s_waitcnt lgkmcnt(0)
	v_add_f32_e32 v2, v2, v3
	v_fmamk_f32 v2, v2, 0x3c800000, v234
	v_mul_f32_e32 v3, 0x4b800000, v2
	v_cmp_gt_f32_e32 vcc, s35, v2
	s_nop 1
	v_cndmask_b32_e32 v2, v2, v3, vcc
	v_rsq_f32_e32 v2, v2
	s_nop 0
	v_mul_f32_e32 v3, 0x45800000, v2
	v_cndmask_b32_e32 v2, v2, v3, vcc
	v_sub_f32_e32 v3, 1.0, v167
	v_mul_f32_e32 v24, v3, v2
	v_mul_f32_e32 v4, v50, v24
	v_mul_f32_e32 v5, v51, v24
	s_waitcnt vmcnt(0)
	v_mul_f32_e32 v4, v34, v4
	v_mul_f32_e32 v5, v35, v5
	v_lshl_add_u64 v[2:3], s[8:9], 0, v[168:169]
	v_cvt_pk_bf16_f32 v4, v4, v5
	v_mul_f32_e32 v5, v52, v24
	v_mul_f32_e32 v16, v53, v24
	v_lshl_add_u64 v[2:3], s[14:15], 1, v[2:3]
	v_mul_f32_e32 v5, v36, v5
	v_mul_f32_e32 v16, v37, v16
	v_cvt_pk_bf16_f32 v5, v5, v16
	v_lshl_add_u64 v[16:17], v[2:3], 0, v[162:163]
	global_store_dwordx2 v[16:17], v[4:5], off
	global_load_dwordx4 v[2:5], v[150:151], off offset:288
	v_mul_f32_e32 v25, v38, v24
	v_mul_f32_e32 v26, v39, v24
	v_mul_f32_e32 v28, v41, v24
	v_mul_f32_e32 v27, v40, v24
	v_mul_f32_e32 v18, v18, v24
	v_mul_f32_e32 v19, v19, v24
	v_mul_f32_e32 v20, v20, v24
	v_mul_f32_e32 v21, v21, v24
	v_mul_f32_e32 v6, v6, v24
	v_mul_f32_e32 v7, v7, v24
	s_and_b32 s14, s0, 0xfe00
	s_ashr_i32 s0, s12, 9
	s_sub_i32 s1, s1, s14
	s_cmpk_gt_i32 s16, 0x3ff
	s_waitcnt vmcnt(0)
	v_mul_f32_e32 v2, v2, v25
	v_mul_f32_e32 v3, v3, v26
	v_cvt_pk_bf16_f32 v2, v2, v3
	v_mul_f32_e32 v3, v5, v28
	v_mul_f32_e32 v4, v4, v27
	v_cvt_pk_bf16_f32 v3, v4, v3
	global_store_dwordx2 v[16:17], v[2:3], off offset:16
	global_load_dwordx4 v[2:5], v[150:151], off offset:320
	v_mul_f32_e32 v25, v42, v24
	v_mul_f32_e32 v26, v43, v24
	v_mul_f32_e32 v27, v44, v24
	v_mul_f32_e32 v28, v45, v24
	s_waitcnt vmcnt(0)
	v_mul_f32_e32 v2, v2, v25
	v_mul_f32_e32 v3, v3, v26
	v_mul_f32_e32 v4, v4, v27
	v_mul_f32_e32 v5, v5, v28
	v_cvt_pk_bf16_f32 v2, v2, v3
	v_cvt_pk_bf16_f32 v3, v4, v5
	global_store_dwordx2 v[16:17], v[2:3], off offset:32
	global_load_dwordx4 v[2:5], v[150:151], off offset:352
	v_mul_f32_e32 v25, v46, v24
	v_mul_f32_e32 v26, v47, v24
	v_mul_f32_e32 v27, v48, v24
	v_mul_f32_e32 v28, v49, v24
	s_waitcnt vmcnt(0)
	v_mul_f32_e32 v2, v2, v25
	v_mul_f32_e32 v3, v3, v26
	v_mul_f32_e32 v4, v4, v27
	v_mul_f32_e32 v5, v5, v28
	v_cvt_pk_bf16_f32 v2, v2, v3
	v_cvt_pk_bf16_f32 v3, v4, v5
	global_store_dwordx2 v[16:17], v[2:3], off offset:48
	global_load_dwordx4 v[2:5], v[150:151], off offset:384
	s_waitcnt vmcnt(0)
	v_mul_f32_e32 v2, v2, v18
	v_mul_f32_e32 v3, v3, v19
	v_mul_f32_e32 v4, v4, v20
	v_mul_f32_e32 v5, v5, v21
	v_cvt_pk_bf16_f32 v2, v2, v3
	v_cvt_pk_bf16_f32 v3, v4, v5
	global_store_dwordx2 v[16:17], v[2:3], off offset:64
	global_load_dwordx4 v[2:5], v[150:151], off offset:416
	v_mul_f32_e32 v18, v22, v24
	v_mul_f32_e32 v19, v23, v24
	s_waitcnt vmcnt(0)
	v_mul_f32_e32 v2, v2, v18
	v_mul_f32_e32 v3, v3, v19
	v_mul_f32_e32 v4, v4, v6
	v_mul_f32_e32 v5, v5, v7
	v_cvt_pk_bf16_f32 v2, v2, v3
	v_cvt_pk_bf16_f32 v3, v4, v5
	global_store_dwordx2 v[16:17], v[2:3], off offset:80
	global_load_dwordx4 v[2:5], v[150:151], off offset:448
	v_mul_f32_e32 v6, v8, v24
	v_mul_f32_e32 v7, v9, v24
	v_mul_f32_e32 v8, v10, v24
	v_mul_f32_e32 v9, v11, v24
	s_waitcnt vmcnt(0)
	v_mul_f32_e32 v2, v6, v2
	v_mul_f32_e32 v3, v7, v3
	v_mul_f32_e32 v4, v8, v4
	v_mul_f32_e32 v5, v9, v5
	v_cvt_pk_bf16_f32 v2, v2, v3
	v_cvt_pk_bf16_f32 v3, v4, v5
	global_store_dwordx2 v[16:17], v[2:3], off offset:96
	global_load_dwordx4 v[2:5], v[150:151], off offset:480
	v_mul_f32_e32 v6, v12, v24
	v_mul_f32_e32 v7, v13, v24
	v_mul_f32_e32 v8, v14, v24
	v_mul_f32_e32 v9, v15, v24
	s_waitcnt vmcnt(0)
	v_mul_f32_e32 v2, v6, v2
	v_mul_f32_e32 v3, v7, v3
	v_mul_f32_e32 v4, v8, v4
	v_mul_f32_e32 v5, v9, v5
	v_cvt_pk_bf16_f32 v2, v2, v3
	v_cvt_pk_bf16_f32 v3, v4, v5
	global_store_dwordx2 v[16:17], v[2:3], off offset:112
	s_cbranch_scc0 .LBB0_1437
	s_or_b32 s14, s0, 16
	s_ashr_i32 s15, s14, 31
	s_and_b32 s16, 0xffff, s1
	s_lshl_b64 s[14:15], s[14:15], 23
	s_add_u32 s12, s54, s14
	s_addc_u32 s14, s55, s15
	s_lshl_b32 s15, s16, 14
	s_add_u32 s15, s12, s15
	s_addc_u32 s17, s14, 0
	s_lshl_b32 s12, s16, 6
	s_and_b32 s12, s12, 0x3c0
	s_lshl_b32 s14, s12, 2
	s_add_u32 s14, s15, s14
	s_addc_u32 s15, s17, 0
	s_lshl_b32 s17, s0, 22
	s_add_u32 s17, s25, s17
	s_addc_u32 s18, s26, 0
	s_lshl_b32 s16, s16, 13
	s_add_u32 s16, s17, s16
	s_addc_u32 s17, s18, 0
	s_mov_b64 s[20:21], 0
	s_mov_b64 s[18:19], s[12:13]
